# local barriers: non-leaders poll the arrival counter directly (no ticket-to-generation hop); generation compares made monotonic (le/gt)
# speedup vs baseline: 1.0083x; 1.0083x over previous
; DEVI unsigned xb_ld(unsigned* p) { return __hip_atomic_load(p, __ATOMIC_RELAXED, __HIP_MEMORY_SCOPE_AGENT); }
; DEVI unsigned xb_add(unsigned* p, unsigned v) { return __hip_atomic_fetch_add(p, v, __ATOMIC_RELAXED, __HIP_MEMORY_SCOPE_AGENT); }
; #define XB_SPIN(cond, bar) do { unsigned _sp = 0; while (cond) { __builtin_amdgcn_s_sleep(1); \
;     if ((++_sp & 255u) == 0u) { if (xb_ld(&(bar)[XB_TMO])) break; if (_sp > XB_SPIN_CAP) { atomicAdd(&(bar)[XB_TMO], 1u); break; } } } } while (0)
; DEVI void xcd_barrier(const XcdBarrier& b) {
;     ...
;     const unsigned old = xb_add(&bar[XB_XSUB(b.x)], 1u);
;     const unsigned gen = old / nloc;
;     if (old + 1u == (gen + 1u) * nloc) {
;       __builtin_amdgcn_fence(__ATOMIC_RELEASE, "agent");
;       asm volatile("s_waitcnt vmcnt(0)" ::: "memory");
;       const unsigned og = xb_add(&bar[XB_TOP], 1u);
;       const unsigned tg = og / nx;
;       if (og + 1u == (tg + 1u) * nx) xb_add(&bar[XB_TOPGEN], 1u);
;       else XB_SPIN(xb_ld(&bar[XB_TOPGEN]) == tg, bar);
;       __builtin_amdgcn_fence(__ATOMIC_ACQUIRE, "agent");
;       xb_add(&bar[XB_XGEN(b.x)], 1u);
;       asm volatile("s_waitcnt vmcnt(0)" ::: "memory");
;     } else {
;       XB_SPIN(xb_ld(&bar[XB_XGEN(b.x)]) == gen, bar);
;       __builtin_amdgcn_fence(__ATOMIC_ACQUIRE, "agent");
;       asm volatile("s_waitcnt vmcnt(0)" ::: "memory");
;     }
.LBB0_947:
	s_or_b64 exec, exec, s[36:37]
	v_cvt_f32_u32_e32 v5, v3
	s_waitcnt vmcnt(0)
	v_readfirstlane_b32 s20, v4
	v_sub_u32_e32 v4, 0, v3
	v_rcp_iflag_f32_e32 v5, v5
	v_add_u32_e32 v6, s20, v0
	v_mul_f32_e32 v5, 0x4f7ffffe, v5
	v_cvt_u32_f32_e32 v5, v5
	v_mul_lo_u32 v0, v4, v5
	v_mul_hi_u32 v0, v5, v0
	v_add_u32_e32 v0, v5, v0
	v_mul_hi_u32 v0, v6, v0
	v_mul_lo_u32 v4, v0, v3
	v_sub_u32_e32 v4, v6, v4
	v_add_u32_e32 v5, 1, v0
	v_cmp_ge_u32_e32 vcc, v4, v3
	s_nop 1
	v_cndmask_b32_e32 v0, v0, v5, vcc
	v_sub_u32_e32 v5, v4, v3
	v_cndmask_b32_e32 v4, v4, v5, vcc
	v_add_u32_e32 v5, 1, v0
	v_cmp_ge_u32_e32 vcc, v4, v3
	v_add_u32_e32 v4, 1, v6
	s_nop 0
	v_cndmask_b32_e32 v0, v0, v5, vcc
	v_mul_lo_u32 v5, v3, v0
	v_add_u32_e32 v3, v5, v3
	v_cmp_ne_u32_e32 vcc, v4, v3
	s_and_saveexec_b64 s[26:27], vcc
	s_xor_b64 s[36:37], exec, s[26:27]
	s_cbranch_execz .LBB0_961
	s_and_b32 s20, s92, 7
	s_cmp_eq_u32 s20, 0
	s_cbranch_scc1 .Lxs_nolocal
	s_cmp_eq_u32 s20, 1
	s_cbranch_scc1 .Lxs_nolocal
	s_cmp_eq_u32 s20, 6
	s_cbranch_scc1 .Lxs_nolocal
	v_readfirstlane_b32 s20, v246
	s_bcnt1_i32_b32 s20, s20
	s_cmp_lg_u32 s20, 1
	s_cbranch_scc1 .Lxs_nolocal
	v_readfirstlane_b32 s20, v247
	s_bcnt1_i32_b32 s20, s20
	s_cmp_lg_u32 s20, 1
	s_cbranch_scc1 .Lxs_nolocal
	v_readfirstlane_b32 s20, v248
	s_bcnt1_i32_b32 s20, s20
	s_cmp_lg_u32 s20, 1
	s_cbranch_scc1 .Lxs_nolocal
	v_readfirstlane_b32 s20, v249
	s_bcnt1_i32_b32 s20, s20
	s_cmp_lg_u32 s20, 1
	s_cbranch_scc1 .Lxs_nolocal
	v_readfirstlane_b32 s20, v250
	s_bcnt1_i32_b32 s20, s20
	s_cmp_lg_u32 s20, 1
	s_cbranch_scc1 .Lxs_nolocal
	v_readfirstlane_b32 s20, v251
	s_bcnt1_i32_b32 s20, s20
	s_cmp_lg_u32 s20, 1
	s_cbranch_scc1 .Lxs_nolocal
	v_readfirstlane_b32 s20, v252
	s_bcnt1_i32_b32 s20, s20
	s_cmp_lg_u32 s20, 1
	s_cbranch_scc1 .Lxs_nolocal
	v_readfirstlane_b32 s20, v253
	s_bcnt1_i32_b32 s20, s20
	s_cmp_lg_u32 s20, 1
	s_cbranch_scc1 .Lxs_nolocal
	v_readlane_b32 s20, v242, 22
	v_readlane_b32 s21, v242, 23
	s_mov_b64 s[38:39], exec
	s_waitcnt lgkmcnt(0)
	s_nop 4
.Lxs_poll:
	global_load_dword v2, v1, s[20:21] sc1
	s_waitcnt vmcnt(0)
	v_cmp_lt_u32_e32 vcc, v2, v3
	s_cbranch_vccz .LBB0_960
	s_sleep 1
	s_branch .Lxs_poll
.Lxs_nolocal:
	v_readlane_b32 s20, v242, 24
	v_readlane_b32 s21, v242, 25
	s_waitcnt lgkmcnt(0)
	s_nop 3
	global_load_dword v2, v1, s[20:21] sc1
	s_waitcnt vmcnt(0)
	v_cmp_le_u32_e32 vcc, v2, v0
	s_and_saveexec_b64 s[38:39], vcc
	s_cbranch_execz .LBB0_960
	s_mov_b32 s20, 1
	s_mov_b64 s[40:41], 0
	s_branch .LBB0_951

; DEVI unsigned xb_ld(unsigned* p) { return __hip_atomic_load(p, __ATOMIC_RELAXED, __HIP_MEMORY_SCOPE_AGENT); }
; #define XB_SPIN(cond, bar) do { unsigned _sp = 0; while (cond) { __builtin_amdgcn_s_sleep(1); \
;     if ((++_sp & 255u) == 0u) { if (xb_ld(&(bar)[XB_TMO])) break; if (_sp > XB_SPIN_CAP) { atomicAdd(&(bar)[XB_TMO], 1u); break; } } } } while (0)
; DEVI void xcd_barrier(const XcdBarrier& b) {
;     ...
;       XB_SPIN(xb_ld(&bar[XB_XGEN(b.x)]) == gen, bar);
;       __builtin_amdgcn_fence(__ATOMIC_ACQUIRE, "agent");
;       asm volatile("s_waitcnt vmcnt(0)" ::: "memory");
.LBB0_955:
	v_readlane_b32 s26, v242, 24
	v_readlane_b32 s27, v242, 25
	s_add_i32 s20, s20, 1
	s_mov_b64 s[46:47], -1
	s_nop 2
	global_load_dword v2, v1, s[26:27] sc1
	s_waitcnt vmcnt(0)
	v_cmp_gt_u32_e32 vcc, v2, v0
	s_orn2_b64 s[44:45], vcc, exec
	s_branch .LBB0_950
